# v17: v15 + MLA K-fragment LDS ring deepened from 4 to 6 buffers (v228-v235 reused)
# speedup vs baseline: 1.0003x; 1.0003x over previous
.LBB0_2717:
	s_mul_i32 s4, s13, 0x3400
	v_add_u32_e32 v227, s4, v184
	ds_read_b128 v[236:239], v227
	ds_read_b128 v[240:243], v227 offset:32
	ds_read_b128 v[244:247], v227 offset:64
	ds_read_b128 v[248:251], v227 offset:96
	ds_read_b128 v[228:231], v227 offset:128
	ds_read_b128 v[232:235], v227 offset:160
	v_max_f32_e32 v193, v48, v48
	v_max_f32_e32 v96, v49, v49
	v_max_f32_e32 v96, v193, v96
	v_max3_f32 v96, v96, v50, v51
	v_max3_f32 v96, v96, v52, v53
	v_max3_f32 v96, v96, v54, v55
	s_waitcnt lgkmcnt(5)
	v_mfma_f32_32x32x16_bf16 v[80:95], v[236:239], v[100:103], 0
	ds_read_b128 v[236:239], v227 offset:6656
	v_max3_f32 v96, v96, v56, v57
	v_max3_f32 v96, v96, v58, v59
	v_max3_f32 v96, v96, v60, v61
	v_max3_f32 v96, v96, v62, v63
	s_waitcnt lgkmcnt(5)
	v_mfma_f32_32x32x16_bf16 v[80:95], v[240:243], v[104:107], v[80:95]
	ds_read_b128 v[240:243], v227 offset:6688
	v_max3_f32 v96, v96, v32, v33
	v_max3_f32 v96, v96, v34, v35
	v_max3_f32 v96, v96, v36, v37
	v_max3_f32 v96, v96, v38, v39
	s_waitcnt lgkmcnt(5)
	v_mfma_f32_32x32x16_bf16 v[80:95], v[244:247], v[108:111], v[80:95]
	ds_read_b128 v[244:247], v227 offset:6720
	v_max3_f32 v96, v96, v40, v41
	v_max3_f32 v96, v96, v42, v43
	v_max3_f32 v96, v96, v44, v45
	v_max3_f32 v96, v96, v46, v47
	v_add_f32_e32 v193, 0x41000000, v191
	v_cmp_gt_f32_e32 vcc, v96, v193
	s_waitcnt lgkmcnt(5)
	v_mfma_f32_32x32x16_bf16 v[80:95], v[248:251], v[112:115], v[80:95]
	ds_read_b128 v[248:251], v227 offset:6752
	s_cbranch_vccz .LBB0_2719
	ds_bpermute_b32 v193, v186, v96
	s_waitcnt lgkmcnt(0)
	v_max3_f32 v193, v191, v96, v193
	v_sub_f32_e32 v96, v191, v193
	v_exp_f32_e32 v96, v96
	v_mov_b32_e32 v191, v193
	v_mul_f32_e32 v192, v192, v96
	v_pk_mul_f32 v[30:31], v[30:31], v[96:97] op_sel_hi:[1,0]
	v_pk_mul_f32 v[28:29], v[28:29], v[96:97] op_sel_hi:[1,0]
	v_pk_mul_f32 v[26:27], v[26:27], v[96:97] op_sel_hi:[1,0]
	v_pk_mul_f32 v[24:25], v[24:25], v[96:97] op_sel_hi:[1,0]
	v_pk_mul_f32 v[22:23], v[22:23], v[96:97] op_sel_hi:[1,0]
	v_pk_mul_f32 v[20:21], v[20:21], v[96:97] op_sel_hi:[1,0]
	v_pk_mul_f32 v[18:19], v[18:19], v[96:97] op_sel_hi:[1,0]
	v_pk_mul_f32 v[16:17], v[16:17], v[96:97] op_sel_hi:[1,0]
	v_pk_mul_f32 v[14:15], v[14:15], v[96:97] op_sel_hi:[1,0]
	v_pk_mul_f32 v[12:13], v[12:13], v[96:97] op_sel_hi:[1,0]
	v_pk_mul_f32 v[10:11], v[10:11], v[96:97] op_sel_hi:[1,0]
	v_pk_mul_f32 v[8:9], v[8:9], v[96:97] op_sel_hi:[1,0]
	v_pk_mul_f32 v[6:7], v[6:7], v[96:97] op_sel_hi:[1,0]
	v_pk_mul_f32 v[4:5], v[4:5], v[96:97] op_sel_hi:[1,0]
	v_pk_mul_f32 v[2:3], v[2:3], v[96:97] op_sel_hi:[1,0]
	v_pk_mul_f32 v[0:1], v[0:1], v[96:97] op_sel_hi:[1,0]
.LBB0_2719:
	v_sub_f32_e32 v48, v48, v191
	v_exp_f32_e32 v193, v48
	v_sub_f32_e32 v48, v49, v191
	v_exp_f32_e32 v195, v48
	s_waitcnt lgkmcnt(5)
	v_mfma_f32_32x32x16_bf16 v[80:95], v[228:231], v[116:119], v[80:95]
	ds_read_b128 v[228:231], v227 offset:6784
	v_sub_f32_e32 v48, v50, v191
	v_exp_f32_e32 v196, v48
	v_sub_f32_e32 v48, v51, v191
	v_exp_f32_e32 v197, v48
	s_waitcnt lgkmcnt(5)
	v_mfma_f32_32x32x16_bf16 v[80:95], v[232:235], v[120:123], v[80:95]
	ds_read_b128 v[232:235], v227 offset:6816
	v_sub_f32_e32 v48, v52, v191
	v_exp_f32_e32 v199, v48
	v_sub_f32_e32 v48, v53, v191
	v_exp_f32_e32 v200, v48
	s_waitcnt lgkmcnt(5)
	v_mfma_f32_32x32x16_bf16 v[64:79], v[236:239], v[100:103], 0
	v_sub_f32_e32 v48, v54, v191
	v_exp_f32_e32 v201, v48
	v_sub_f32_e32 v48, v55, v191
	v_exp_f32_e32 v202, v48
	s_waitcnt lgkmcnt(4)
	v_mfma_f32_32x32x16_bf16 v[64:79], v[240:243], v[104:107], v[64:79]
	v_sub_f32_e32 v48, v56, v191
	v_exp_f32_e32 v203, v48
	v_sub_f32_e32 v48, v57, v191
	v_exp_f32_e32 v204, v48
	s_waitcnt lgkmcnt(3)
	v_mfma_f32_32x32x16_bf16 v[64:79], v[244:247], v[108:111], v[64:79]
	v_sub_f32_e32 v48, v58, v191
	v_exp_f32_e32 v205, v48
	v_sub_f32_e32 v48, v59, v191
	v_sub_f32_e32 v32, v32, v191
	s_waitcnt lgkmcnt(2)
	v_mfma_f32_32x32x16_bf16 v[64:79], v[248:251], v[112:115], v[64:79]
	s_mul_i32 s20, s12, 0x2400
	v_exp_f32_e32 v206, v48
	v_sub_f32_e32 v48, v60, v191
	v_exp_f32_e32 v211, v32
	v_sub_f32_e32 v32, v33, v191
	s_waitcnt lgkmcnt(1)
	v_mfma_f32_32x32x16_bf16 v[64:79], v[228:231], v[116:119], v[64:79]
	v_lshlrev_b32_e32 v33, 1, v185
	v_lshlrev_b32_e32 v96, 1, v160
	v_exp_f32_e32 v207, v48
	v_sub_f32_e32 v48, v61, v191
	s_waitcnt lgkmcnt(0)
	v_mfma_f32_32x32x16_bf16 v[64:79], v[232:235], v[120:123], v[64:79]
	v_add3_u32 v52, s20, v33, v96
	v_exp_f32_e32 v208, v48
	v_sub_f32_e32 v48, v62, v191
	v_add_u32_e32 v58, 0xa800, v52
	v_exp_f32_e32 v209, v48
	v_sub_f32_e32 v48, v63, v191
	v_add_u32_e32 v56, 0x9800, v52
	ds_read_b64 v[52:53], v58 offset:1536
	ds_read_b64 v[54:55], v58 offset:1552
	v_exp_f32_e32 v210, v48
	ds_read_b64 v[48:49], v56 offset:1024
	ds_read_b64 v[50:51], v56 offset:1040
	v_sub_f32_e32 v36, v36, v191
	v_exp_f32_e32 v212, v32
	v_sub_f32_e32 v32, v34, v191
	v_exp_f32_e32 v215, v36
	v_sub_f32_e32 v36, v37, v191
	v_exp_f32_e32 v213, v32
	v_sub_f32_e32 v57, v35, v191
	v_cvt_pk_bf16_f32 v32, v193, v195
	v_cvt_pk_bf16_f32 v33, v196, v197
	v_cvt_pk_bf16_f32 v34, v199, v200
	v_cvt_pk_bf16_f32 v35, v201, v202
	v_exp_f32_e32 v216, v36
	v_sub_f32_e32 v36, v38, v191
	s_waitcnt lgkmcnt(2)
	v_mfma_f32_32x32x16_bf16 v[0:15], v[52:55], v[32:35], v[0:15]
	v_exp_f32_e32 v217, v36
	v_sub_f32_e32 v52, v39, v191
	ds_read_b64 v[36:37], v58 offset:1568
	ds_read_b64 v[38:39], v58 offset:1584
	v_sub_f32_e32 v40, v40, v191
	v_exp_f32_e32 v214, v57
	v_exp_f32_e32 v218, v52
	v_exp_f32_e32 v219, v40
	s_waitcnt lgkmcnt(2)
	v_mfma_f32_32x32x16_bf16 v[16:31], v[48:51], v[32:35], v[16:31]
	ds_read_b64 v[48:49], v56 offset:1056
	ds_read_b64 v[50:51], v56 offset:1072
	v_cvt_pk_bf16_f32 v32, v203, v204
	v_cvt_pk_bf16_f32 v33, v205, v206
	v_cvt_pk_bf16_f32 v34, v207, v208
	v_cvt_pk_bf16_f32 v35, v209, v210
	v_sub_f32_e32 v40, v41, v191
	v_exp_f32_e32 v220, v40
	s_waitcnt lgkmcnt(2)
	v_mfma_f32_32x32x16_bf16 v[0:15], v[36:39], v[32:35], v[0:15]
	ds_read_b64 v[36:37], v58 offset:1600
	ds_read_b64 v[38:39], v58 offset:1616
	v_sub_f32_e32 v40, v42, v191
	v_exp_f32_e32 v221, v40
	v_sub_f32_e32 v40, v43, v191
	v_exp_f32_e32 v222, v40
	v_sub_f32_e32 v40, v44, v191
	v_exp_f32_e32 v223, v40
	s_waitcnt lgkmcnt(2)
	v_mfma_f32_32x32x16_bf16 v[16:31], v[48:51], v[32:35], v[16:31]
	ds_read_b64 v[48:49], v56 offset:1088
	ds_read_b64 v[50:51], v56 offset:1104
	v_cvt_pk_bf16_f32 v32, v211, v212
	v_cvt_pk_bf16_f32 v33, v213, v214
	v_cvt_pk_bf16_f32 v34, v215, v216
	v_cvt_pk_bf16_f32 v35, v217, v218
	v_sub_f32_e32 v40, v45, v191
	v_exp_f32_e32 v224, v40
	ds_read_b64 v[40:41], v56 offset:1120
	ds_read_b64 v[42:43], v56 offset:1136
	s_waitcnt lgkmcnt(4)
	v_mfma_f32_32x32x16_bf16 v[0:15], v[36:39], v[32:35], v[0:15]
	ds_read_b64 v[36:37], v58 offset:1632
	ds_read_b64 v[38:39], v58 offset:1648
	v_sub_f32_e32 v44, v46, v191
	v_exp_f32_e32 v225, v44
	s_add_i32 s4, s16, -4
	s_cmp_ge_u32 s4, s9
	s_waitcnt lgkmcnt(0)
	s_barrier
	v_mfma_f32_32x32x16_bf16 v[16:31], v[48:51], v[32:35], v[16:31]
	v_sub_f32_e32 v32, v47, v191
	v_exp_f32_e32 v226, v32
	v_cvt_pk_bf16_f32 v32, v219, v220
	v_cvt_pk_bf16_f32 v33, v221, v222
	v_cvt_pk_bf16_f32 v34, v223, v224
	v_cvt_pk_bf16_f32 v35, v225, v226
	s_nop 1
	v_mfma_f32_32x32x16_bf16 v[16:31], v[40:43], v[32:35], v[16:31]
	v_mfma_f32_32x32x16_bf16 v[0:15], v[36:39], v[32:35], v[0:15]
	s_cbranch_scc1 .LBB0_2726
	s_mul_i32 s21, s12, 0x3400
	v_add3_u32 v32, s21, v190, v198
	s_waitcnt vmcnt(1)
	ds_write_b128 v32, v[128:131]
	s_and_saveexec_b64 s[4:5], s[10:11]
	v_lshlrev_b32_e32 v32, 1, v180
	v_lshlrev_b32_e32 v33, 1, v142
	v_add3_u32 v32, s21, v32, v33
	ds_write_b128 v32, v[124:127]
	s_or_b64 exec, exec, s[4:5]
	v_lshlrev_b32_e32 v32, 1, v182
	v_add3_u32 v32, s20, v32, v158
	s_cmp_ge_u32 s16, s8
	s_waitcnt vmcnt(0)
	ds_write_b128 v32, v[132:135] offset:39936
	s_cbranch_scc1 .LBB0_2726
	v_lshl_add_u64 v[32:33], s[90:91], 0, v[178:179]
	v_add_co_u32_e32 v32, vcc, 0x159c0000, v32
	s_nop 1
	v_addc_co_u32_e32 v33, vcc, 0, v33, vcc
	global_load_dwordx4 v[128:131], v[32:33], off
	s_and_saveexec_b64 s[4:5], s[10:11]
	s_cbranch_execz .LBB0_2725
	v_lshl_add_u64 v[32:33], s[90:91], 0, v[176:177]
	v_add_co_u32_e32 v32, vcc, 0x159c0000, v32
	s_nop 1
	v_addc_co_u32_e32 v33, vcc, 0, v33, vcc
	global_load_dwordx4 v[124:127], v[32:33], off

.LBB0_2726:
	v_add_u32_e32 v198, s19, v184
	ds_read_b128 v[236:239], v198
	ds_read_b128 v[240:243], v198 offset:32
	ds_read_b128 v[244:247], v198 offset:64
	ds_read_b128 v[248:251], v198 offset:96
	ds_read_b128 v[228:231], v198 offset:128
	ds_read_b128 v[232:235], v198 offset:160
.LBB0_2728:
	v_add_f32_e32 v193, 0, v193
	v_add_f32_e32 v195, 0, v195
	v_add_f32_e32 v193, v196, v193
	v_add_f32_e32 v195, v197, v195
	s_waitcnt lgkmcnt(5)
	v_mfma_f32_32x32x16_bf16 v[48:63], v[236:239], v[100:103], 0
	ds_read_b128 v[236:239], v198 offset:6656
	v_add_f32_e32 v193, v199, v193
	v_add_f32_e32 v195, v200, v195
	v_add_f32_e32 v193, v201, v193
	v_add_f32_e32 v195, v202, v195
	s_waitcnt lgkmcnt(5)
	v_mfma_f32_32x32x16_bf16 v[48:63], v[240:243], v[104:107], v[48:63]
	ds_read_b128 v[240:243], v198 offset:6688
	v_add_f32_e32 v193, v203, v193
	v_add_f32_e32 v195, v204, v195
	v_add_f32_e32 v193, v205, v193
	v_add_f32_e32 v195, v206, v195
	s_waitcnt lgkmcnt(5)
	v_mfma_f32_32x32x16_bf16 v[48:63], v[244:247], v[108:111], v[48:63]
	ds_read_b128 v[244:247], v198 offset:6720
	v_add_f32_e32 v193, v207, v193
	v_add_f32_e32 v195, v208, v195
	v_add_f32_e32 v193, v209, v193
	v_add_f32_e32 v195, v210, v195
	s_waitcnt lgkmcnt(5)
	v_mfma_f32_32x32x16_bf16 v[48:63], v[248:251], v[112:115], v[48:63]
	ds_read_b128 v[248:251], v198 offset:6752
	v_add_f32_e32 v193, v211, v193
	v_add_f32_e32 v195, v212, v195
	v_add_f32_e32 v193, v213, v193
	v_add_f32_e32 v195, v214, v195
	s_waitcnt lgkmcnt(5)
	v_mfma_f32_32x32x16_bf16 v[48:63], v[228:231], v[116:119], v[48:63]
	ds_read_b128 v[228:231], v198 offset:6784
	v_add_f32_e32 v193, v215, v193
	v_add_f32_e32 v195, v216, v195
	v_add_f32_e32 v193, v217, v193
	v_add_f32_e32 v195, v218, v195
	s_waitcnt lgkmcnt(5)
	v_mfma_f32_32x32x16_bf16 v[48:63], v[232:235], v[120:123], v[48:63]
	ds_read_b128 v[232:235], v198 offset:6816
	v_add_f32_e32 v193, v219, v193
	v_add_f32_e32 v195, v220, v195
	v_add_f32_e32 v193, v221, v193
	v_add_f32_e32 v195, v222, v195
	s_waitcnt lgkmcnt(5)
	v_mfma_f32_32x32x16_bf16 v[32:47], v[236:239], v[100:103], 0
	v_add_f32_e32 v193, v223, v193
	v_add_f32_e32 v195, v224, v195
	v_add_f32_e32 v193, v225, v193
	v_add_f32_e32 v195, v226, v195
	s_waitcnt lgkmcnt(4)
	v_mfma_f32_32x32x16_bf16 v[32:47], v[240:243], v[104:107], v[32:47]
	v_add_f32_e32 v193, v195, v193
	v_add_f32_e32 v192, v192, v193
	v_max_f32_e32 v193, v81, v81
	v_max_f32_e32 v195, v80, v80
	s_waitcnt lgkmcnt(3)
	v_mfma_f32_32x32x16_bf16 v[32:47], v[244:247], v[108:111], v[32:47]
	v_max_f32_e32 v193, v195, v193
	v_max3_f32 v193, v193, v82, v83
	v_max3_f32 v193, v193, v84, v85
	v_max3_f32 v193, v193, v86, v87
	s_waitcnt lgkmcnt(2)
	v_mfma_f32_32x32x16_bf16 v[32:47], v[248:251], v[112:115], v[32:47]
	v_max3_f32 v193, v193, v88, v89
	v_max3_f32 v193, v193, v90, v91
	v_max3_f32 v193, v193, v92, v93
	v_max3_f32 v193, v193, v94, v95
	s_waitcnt lgkmcnt(1)
	v_mfma_f32_32x32x16_bf16 v[32:47], v[228:231], v[116:119], v[32:47]
	v_max3_f32 v193, v193, v64, v65
	v_max3_f32 v193, v193, v66, v67
	v_max3_f32 v193, v193, v68, v69
	v_max3_f32 v193, v193, v70, v71
	s_waitcnt lgkmcnt(0)
	v_mfma_f32_32x32x16_bf16 v[32:47], v[232:235], v[120:123], v[32:47]
	v_max3_f32 v193, v193, v72, v73
	v_max3_f32 v193, v193, v74, v75
	v_max3_f32 v193, v193, v76, v77
	v_max3_f32 v193, v193, v78, v79
	v_add_f32_e32 v195, 0x41000000, v191
	v_cmp_gt_f32_e32 vcc, v193, v195
	s_cbranch_vccz .LBB0_2730
	ds_bpermute_b32 v195, v186, v193
	s_waitcnt lgkmcnt(0)
	v_max3_f32 v193, v191, v193, v195
	v_sub_f32_e32 v191, v191, v193
	v_exp_f32_e32 v196, v191
	v_mov_b32_e32 v191, v193
	v_mul_f32_e32 v192, v192, v196
	v_pk_mul_f32 v[30:31], v[30:31], v[196:197] op_sel_hi:[1,0]
	v_pk_mul_f32 v[28:29], v[28:29], v[196:197] op_sel_hi:[1,0]
	v_pk_mul_f32 v[26:27], v[26:27], v[196:197] op_sel_hi:[1,0]
	v_pk_mul_f32 v[24:25], v[24:25], v[196:197] op_sel_hi:[1,0]
	v_pk_mul_f32 v[22:23], v[22:23], v[196:197] op_sel_hi:[1,0]
	v_pk_mul_f32 v[20:21], v[20:21], v[196:197] op_sel_hi:[1,0]
	v_pk_mul_f32 v[18:19], v[18:19], v[196:197] op_sel_hi:[1,0]
	v_pk_mul_f32 v[16:17], v[16:17], v[196:197] op_sel_hi:[1,0]
	v_pk_mul_f32 v[14:15], v[14:15], v[196:197] op_sel_hi:[1,0]
	v_pk_mul_f32 v[12:13], v[12:13], v[196:197] op_sel_hi:[1,0]
	v_pk_mul_f32 v[10:11], v[10:11], v[196:197] op_sel_hi:[1,0]
	v_pk_mul_f32 v[8:9], v[8:9], v[196:197] op_sel_hi:[1,0]
	v_pk_mul_f32 v[6:7], v[6:7], v[196:197] op_sel_hi:[1,0]
	v_pk_mul_f32 v[4:5], v[4:5], v[196:197] op_sel_hi:[1,0]
	v_pk_mul_f32 v[2:3], v[2:3], v[196:197] op_sel_hi:[1,0]
	v_pk_mul_f32 v[0:1], v[0:1], v[196:197] op_sel_hi:[1,0]
